# v050 plus slc loop: block-list byte carried across iterations and the selection-mask word read issued at the loop top (one LDS round trip per tile instead of three)
# speedup vs baseline: 1.0089x; 1.0025x over previous
; DI float bf2f(bf16_t v) { return __uint_as_float(((unsigned)v) << 16); }
; DI float sigmoid_f(float x) { return 1.f / (1.f + __expf(-x)); }
; DI void slc_unit(const Params& P, lptr L, int u, int tid, int lane, int wid) {
;     ...
;     int NTS = 0;
; #pragma unroll
;     for (int k = 0; k < 8; ++k) NTS += __popc(un[k]);
;     __syncthreads();
;     bf16x8 qf[4]; load_q(qf, PROJ + row * PROJ_LD + 1024 + head * 64, hi);
;     const float gs = sigmoid_f(bf2f(PROJ[row * PROJ_LD + 1792 + head * 3 + 1]));
;     f32x16 o0, o1;
; #pragma unroll
;     for (int r = 0; r < 16; ++r) { o0[r] = 0.f; o1[r] = 0.f; }
;     RowState rs; rs.mref = 0.f; rs.l = 0.f; rs.seen = false;
;     const bf16_t* kb_ = PROJ + (size_t)(b * SEQ) * PROJ_LD + 1536 + g * 64; const size_t kpitch_ = PROJ_LD;
;     const bf16_t* vb_ = VT + (size_t)((b * 12 + 8 + g) * 64) * VTP; const size_t vpitch_ = VTP;
;     ATT_LOOP_BEGIN(NTS, false, kb_ + (size_t)((int)list[jt] * 64) * PROJ_LD, vb_ + (size_t)((int)list[jt]) * 64, (const float*)nullptr)
;         const int j = (int)list[jt], kv0 = j * 64;
;         const bool sel = (sm[ql * 8 + (j >> 5)] >> (j & 31)) & 1u;
.LBB0_609:
	s_or_b64 exec, exec, s[2:3]
	s_not_b32 s2, s47
	s_lshl_b32 s2, s2, 3
	ds_read_b128 v[2:5], v1 offset:37376
	ds_read_b128 v[6:9], v1 offset:37392
	s_and_b32 s2, s2, 0x3fc0
	v_add_u32_e32 v91, s2, v179
	v_readlane_b32 s2, v251, 58
	v_readlane_b32 s3, v251, 59
	v_add_u32_e32 v90, s50, v91
	s_waitcnt lgkmcnt(1)
	v_bcnt_u32_b32 v10, v4, 0
	v_bcnt_u32_b32 v11, v5, 0
	v_mov_b64_e32 v[4:5], s[2:3]
	s_movk_i32 s2, 0x1080
	v_bcnt_u32_b32 v3, v3, 0
	v_mad_u64_u32 v[4:5], s[2:3], v90, s2, v[4:5]
	v_bcnt_u32_b32 v2, v2, 0
	s_lshl_b32 s82, s51, 1
	s_lshl_b32 s2, s49, 1
	s_mov_b32 s3, s83
	v_add_u32_e32 v2, v3, v2
	s_waitcnt lgkmcnt(0)
	v_bcnt_u32_b32 v12, v6, 0
	v_bcnt_u32_b32 v13, v7, 0
	v_lshl_add_u64 v[6:7], v[4:5], 0, s[82:83]
	v_lshl_add_u64 v[4:5], v[4:5], 0, s[2:3]
	v_add_u32_e32 v2, v2, v10
	s_add_i32 s2, s33, s48
	v_add_u32_e32 v2, v2, v11
	s_mul_i32 s2, s2, 0x202000
	v_add_u32_e32 v2, v2, v12
	s_add_i32 s2, s2, 0x1010000
	v_readlane_b32 s3, v251, 60
	v_bcnt_u32_b32 v8, v8, 0
	v_add_u32_e32 v2, v2, v13
	s_add_u32 s22, s3, s2
	v_readlane_b32 s2, v251, 61
	v_bcnt_u32_b32 v9, v9, 0
	v_mov_b32_e32 v153, v1
	v_add_u32_e32 v2, v2, v8
	s_addc_u32 s23, s2, 0
	s_add_i32 s2, 0, 0x1a104
	v_lshl_add_u64 v[6:7], v[6:7], 0, v[152:153]
	v_add_u32_e32 v99, v2, v9
	v_mov_b32_e32 v2, s2
	s_barrier
	global_load_dwordx4 v[66:69], v[6:7], off offset:2048
	global_load_dwordx4 v[70:73], v[6:7], off offset:2080
	global_load_dwordx4 v[74:77], v[6:7], off offset:2112
	global_load_dwordx4 v[78:81], v[6:7], off offset:2144
	global_load_ushort v98, v[4:5], off offset:3586
	ds_read_u8 v4, v2
	s_mov_b32 s2, 0x42000
	v_mov_b32_e32 v3, v1
	v_mov_b32_e32 v163, v1
	v_mov_b32_e32 v5, v1
	s_waitcnt lgkmcnt(0)
	v_mul_lo_u32 v2, v4, s2
	v_mov_b32_e32 v253, v4
	v_lshl_add_u64 v[2:3], s[0:1], 0, v[2:3]
	v_lshlrev_b32_e32 v4, 7, v4
	v_lshl_add_u64 v[2:3], v[2:3], 0, v[162:163]
	v_lshl_add_u64 v[4:5], s[22:23], 0, v[4:5]
	v_lshl_add_u64 v[2:3], v[2:3], 0, v[0:1]
	v_mov_b32_e32 v161, v1
	global_load_dwordx4 v[82:85], v[2:3], off offset:3072
	v_lshl_add_u64 v[2:3], v[4:5], 0, v[160:161]
	v_lshl_add_u64 v[2:3], v[2:3], 0, v[0:1]
	global_load_dwordx4 v[86:89], v[2:3], off
	v_cmp_eq_u32_e32 vcc, 0, v99
	s_and_b64 vcc, exec, vcc
	s_waitcnt vmcnt(1)
	ds_write_b128 v127, v[82:85]
	s_waitcnt vmcnt(0)
	ds_write_b128 v127, v[86:89] offset:18432
	s_waitcnt lgkmcnt(0)
	s_barrier
	s_cbranch_vccnz .LBB0_623
	v_lshl_add_u64 v[2:3], s[22:23], 0, v[160:161]
	v_mov_b32_e32 v14, v1
	v_mov_b32_e32 v15, v1
	v_lshl_add_u64 v[92:93], v[2:3], 0, v[0:1]
	v_mov_b32_e32 v0, v1
	v_mov_b32_e32 v2, v1
	v_mov_b32_e32 v3, v1
	v_mov_b32_e32 v4, v1
	v_mov_b32_e32 v5, v1
	v_mov_b32_e32 v6, v1
	v_mov_b32_e32 v7, v1
	v_mov_b32_e32 v8, v1
	v_mov_b32_e32 v9, v1
	v_mov_b32_e32 v10, v1
	v_mov_b32_e32 v11, v1
	v_mov_b32_e32 v12, v1
	v_mov_b32_e32 v13, v1
	v_mov_b64_e32 v[32:33], v[14:15]
	v_mov_b64_e32 v[30:31], v[12:13]
	v_mov_b64_e32 v[28:29], v[10:11]
	v_mov_b64_e32 v[26:27], v[8:9]
	v_mov_b64_e32 v[24:25], v[6:7]
	v_mov_b64_e32 v[22:23], v[4:5]
	v_mov_b64_e32 v[20:21], v[2:3]
	v_mov_b64_e32 v[18:19], v[0:1]
	v_mov_b64_e32 v[16:17], v[14:15]
	v_mov_b32_e32 v94, v150
	v_mov_b32_e32 v95, v150
	s_mov_b32 s0, 0
	v_mov_b32_e32 v96, v150
	v_mov_b32_e32 v97, v150
	s_mov_b64 s[22:23], 0
	v_mov_b32_e32 v100, 0
	v_mov_b64_e32 v[14:15], v[12:13]
	v_mov_b64_e32 v[12:13], v[10:11]
	v_mov_b64_e32 v[10:11], v[8:9]
	v_mov_b64_e32 v[8:9], v[6:7]
	v_mov_b64_e32 v[6:7], v[4:5]
	v_mov_b64_e32 v[4:5], v[2:3]
	v_mov_b64_e32 v[2:3], v[0:1]
	v_mov_b32_e32 v101, 0
.LBB0_611:
	s_add_i32 s30, s0, 1
	v_cmp_ge_u32_e64 s[24:25], s30, v99
	v_cmp_lt_u32_e64 s[26:27], s30, v99
	v_lshrrev_b32_e32 v34, 3, v253
	v_and_b32_e32 v34, 28, v34
	v_add_u32_e32 v34, v186, v34
	ds_read_b32 v255, v34
	s_and_b64 vcc, exec, s[24:25]
	s_cbranch_vccnz .LBB0_613
	s_add_i32 s1, s0, 0
	s_add_i32 s1, s1, 0x1a105
	v_mov_b32_e32 v0, s1
	ds_read_u8 v254, v0
	s_mov_b32 s1, 0x42000
	v_mov_b32_e32 v35, v1
	s_waitcnt lgkmcnt(0)
	v_mul_lo_u32 v0, v254, s1
	v_lshlrev_b32_e32 v34, 7, v254
	v_lshl_add_u64 v[36:37], v[156:157], 0, v[0:1]
	v_lshl_add_u64 v[34:35], v[92:93], 0, v[34:35]
	global_load_dwordx4 v[82:85], v[36:37], off offset:3072
	global_load_dwordx4 v[86:89], v[34:35], off
.LBB0_613:
	v_mov_b32_e32 v0, v253
	s_and_b32 s31, s0, 1
	v_and_b32_e32 v35, 31, v253
	s_waitcnt lgkmcnt(0)
	v_lshrrev_b32_e32 v36, v0, v255
	v_bfe_u32 v34, v255, v35, 1
	v_and_b32_e32 v35, 1, v36
	v_mov_b32_e32 v253, v254
	v_cmp_ne_u32_e32 vcc, 0, v34
	v_cmp_eq_u32_e64 s[28:29], 1, v35
	s_cbranch_vccz .LBB0_618
; DI void qk_acc(lptr Kt, const bf16x8 (&qf)[4], f32x16& s0, f32x16& s1, int lane) {
;     const int i = lane & 31, hi = lane >> 5;
;     const int krow = (i & 19) | ((i & 4) << 1) | ((i & 8) >> 1);
;     lptr kp = Kt + krow * KPB + hi * 16;
;     bf16x8 a0[4], a1[4];
; #pragma unroll
;     for (int d0 = 0; d0 < 4; ++d0) { a0[d0] = *(LAS bf16x8*)(kp + d0 * 32); a1[d0] = *(LAS bf16x8*)(kp + 32 * KPB + d0 * 32); }
;     __builtin_amdgcn_s_setprio(1);
; template <int MODE>
; DI void bias_init(f32x16& s0, f32x16& s1, const TP& tp, float fbm, int hi) {
; #pragma unroll
;     for (int r = 0; r < 16; ++r) {
;         const int kvc = 16 * (r >> 3) + (r & 7);
;         if (MODE == 0) { s0[r] = __builtin_fmaf(-L2E, tp.cs[kvc + 8 * hi], fbm); s1[r] = __builtin_fmaf(-L2E, tp.cs[kvc + 32 + 8 * hi], fbm); }
;         else { s0[r] = __builtin_fmaf(tp.sl, (float)kvc, fbm); s1[r] = __builtin_fmaf(tp.sl, (float)(kvc + 32), fbm); }
;     }
; }
; DI float max3_asm(float a, float b, float c) { float r; asm("v_max3_f32 %0, %1, %2, %3" : "=v"(r) : "v"(a), "v"(b), "v"(c)); return r; }
; template <bool MASK>
; DI float mask_rowmax(f32x16& s0, f32x16& s1, const TP& tp) {
;     if (MASK) {
; #pragma unroll
;         for (int r = 0; r < 16; ++r) {
;             const int kvc = 16 * (r >> 3) + (r & 7);
;             const bool v0 = tp.sel && (kvc <= tp.lim) && (kvc > tp.lim2), v1 = tp.sel && (kvc + 32 <= tp.lim) && (kvc + 32 > tp.lim2);
;             s0[r] = v0 ? s0[r] : -1e30f; s1[r] = v1 ? s1[r] : -1e30f;
;         }
;     }
;     const float seed = __builtin_fminf(s0[15], s1[15]);
;     float ma = seed, mb = seed;
; #pragma unroll
;     for (int r = 0; r < 16; r += 2) { ma = max3_asm(ma, s0[r], s1[r]); mb = max3_asm(mb, s0[r + 1], s1[r + 1]); }
;     const float mx = fmaxf(ma, mb);
;     return fmaxf(mx, __shfl_xor(mx, 32));
; }
; template <int MODE, bool MASK, bool WITH_O>
; DI void attn_tile_t(lptr Kt, lptr Vt, const bf16x8 (&qf)[4], f32x16& o0, f32x16& o1, RowState& rs, const TP& tp, int lane) {
;     const int hi = lane >> 5;
;     f32x16 s0, s1;
;     bias_init<MODE>(s0, s1, tp, tp.fb - rs.mref, hi);
;     qk_acc(Kt, qf, s0, s1, lane);
;     const float mx = mask_rowmax<MASK>(s0, s1, tp);
;     const bool was = rs.seen; rs.seen = was || (mx > -1e29f);
;     const bool trig = (mx > 8.f) || (!was && mx > -1e29f && mx < -8.f);
;     if (__builtin_expect(__any(trig), 0)) {
	v_lshl_or_b32 v0, v0, 6, v126
	v_sub_u32_e32 v34, v0, v91
	v_cvt_f32_i32_e32 v34, v34
	s_mov_b32 s0, 2.0
	v_sub_u32_e32 v152, v91, v0
	s_mov_b32 s1, 0x40400000
	v_cmp_lt_i32_e32 vcc, 54, v152
	v_fma_f32 v0, v150, v34, -v101
	s_cmp_eq_u64 vcc, exec
	s_cselect_b64 s[98:99], -1, 0
	s_orn2_b64 s[100:101], s[28:29], s[98:99]
	v_cndmask_b32_e64 v0, v210, v0, s[100:101]
	v_pk_fma_f32 v[36:37], v[94:95], s[0:1], v[0:1] op_sel_hi:[1,1,0]
	s_mov_b32 s0, 4.0
	s_mov_b32 s1, 0x40a00000
	v_pk_fma_f32 v[38:39], v[94:95], s[0:1], v[0:1] op_sel_hi:[1,1,0]
	s_mov_b32 s0, 0x40c00000
	s_mov_b32 s1, 0x40e00000
	v_pk_fma_f32 v[40:41], v[94:95], s[0:1], v[0:1] op_sel_hi:[1,1,0]
	s_mov_b32 s0, 0x41800000
	s_mov_b32 s1, 0x41880000
	v_pk_fma_f32 v[42:43], v[94:95], s[0:1], v[0:1] op_sel_hi:[1,1,0]
	s_mov_b32 s0, 0x41900000
	s_mov_b32 s1, 0x41980000
	v_pk_fma_f32 v[44:45], v[94:95], s[0:1], v[0:1] op_sel_hi:[1,1,0]
	s_mov_b32 s0, 0x41a00000
	s_mul_i32 s33, s31, 0x2400
	s_mov_b32 s1, 0x41a80000
	v_mov_b32_e32 v151, v150
	v_fma_f32 v34, 0, v150, v0
	v_add_f32_e32 v35, v150, v0
	v_pk_fma_f32 v[46:47], v[94:95], s[0:1], v[0:1] op_sel_hi:[1,1,0]
	v_pk_fma_f32 v[48:49], v[94:95], s[18:19], v[0:1] op_sel_hi:[1,1,0]
	v_pk_fma_f32 v[64:65], v[150:151], s[4:5], v[0:1] op_sel_hi:[1,1,0]
	v_pk_fma_f32 v[62:63], v[150:151], s[14:15], v[0:1] op_sel_hi:[1,1,0]
	v_pk_fma_f32 v[60:61], v[150:151], s[16:17], v[0:1] op_sel_hi:[1,1,0]
	v_pk_fma_f32 v[58:59], v[150:151], s[94:95], v[0:1] op_sel_hi:[1,1,0]
	v_pk_fma_f32 v[56:57], v[150:151], s[96:97], v[0:1] op_sel_hi:[1,1,0]
	v_pk_fma_f32 v[54:55], v[150:151], s[84:85], v[0:1] op_sel_hi:[1,1,0]
	v_pk_fma_f32 v[52:53], v[150:151], s[72:73], v[0:1] op_sel_hi:[1,1,0]
	v_pk_fma_f32 v[50:51], v[96:97], s[44:45], v[0:1] op_sel_hi:[1,1,0]
	v_add_u32_e32 v0, s33, v170
	ds_read_b128 v[102:105], v0 offset:4608
	ds_read_b128 v[106:109], v0
	ds_read_b128 v[110:113], v0 offset:32
	ds_read_b128 v[114:117], v0 offset:4640
	ds_read_b128 v[118:121], v0 offset:64
	ds_read_b128 v[158:161], v0 offset:4672
	ds_read_b128 v[162:165], v0 offset:96
	ds_read_b128 v[166:169], v0 offset:4704
	s_setprio 1
	s_waitcnt lgkmcnt(6)
	v_mfma_f32_32x32x16_bf16 v[34:49], v[106:109], v[66:69], v[34:49]
	v_mfma_f32_32x32x16_bf16 v[50:65], v[102:105], v[66:69], v[50:65]
	s_waitcnt lgkmcnt(5)
	v_mfma_f32_32x32x16_bf16 v[34:49], v[110:113], v[70:73], v[34:49]
	s_waitcnt lgkmcnt(4)
	v_mfma_f32_32x32x16_bf16 v[50:65], v[114:117], v[70:73], v[50:65]
	s_waitcnt lgkmcnt(3)
	v_mfma_f32_32x32x16_bf16 v[34:49], v[118:121], v[74:77], v[34:49]
	s_waitcnt lgkmcnt(2)
	v_mfma_f32_32x32x16_bf16 v[50:65], v[158:161], v[74:77], v[50:65]
	s_waitcnt lgkmcnt(1)
	v_mfma_f32_32x32x16_bf16 v[34:49], v[162:165], v[78:81], v[34:49]
	s_waitcnt lgkmcnt(0)
	v_mfma_f32_32x32x16_bf16 v[50:65], v[166:169], v[78:81], v[50:65]
	s_setprio 0
	s_and_b64 vcc, exec, s[98:99]
	s_cbranch_vccz .Lslc_masked
	s_nop 10
	v_max_f32_e32 v252, v65, v65
	v_max_f32_e32 v228, v49, v49
	v_min_f32_e32 v252, v228, v252
	v_max3_f32 v228, v252, v34, v50
	v_max3_f32 v252, v252, v35, v51
	s_mov_b32 s0, 0xefa18f08
	v_max3_f32 v228, v228, v36, v52
	v_max3_f32 v252, v252, v37, v53
	s_nop 0
	v_max3_f32 v228, v228, v38, v54
	v_max3_f32 v252, v252, v39, v55
	s_nop 0
	v_max3_f32 v228, v228, v40, v56
	v_max3_f32 v252, v252, v41, v57
	s_nop 0
	v_max3_f32 v228, v228, v42, v58
	v_max3_f32 v252, v252, v43, v59
	s_nop 0
	v_max3_f32 v228, v228, v44, v60
	v_max3_f32 v252, v252, v45, v61
	s_nop 0
	v_max3_f32 v228, v228, v46, v62
	v_max3_f32 v252, v252, v47, v63
	s_nop 0
	v_max3_f32 v228, v228, v48, v64
	v_max3_f32 v252, v252, v49, v65
	s_nop 0
	v_max_f32_e32 v252, v252, v252
	v_max_f32_e32 v228, v228, v228
	v_max_f32_e32 v252, v228, v252
	ds_bpermute_b32 v228, v149, v252
	s_waitcnt lgkmcnt(0)
	v_max_f32_e32 v228, v228, v228
	v_max_f32_e32 v252, v252, v228
	v_cmp_lt_f32_e64 s[28:29], s0, v252
	s_mov_b32 s0, 0x41000000
	v_cmp_lt_f32_e32 vcc, s0, v252
	s_mov_b32 s0, 0xc1000000
	v_cmp_gt_f32_e64 s[0:1], s0, v252
	s_and_b64 s[0:1], s[0:1], s[28:29]
	s_andn2_b64 s[0:1], s[0:1], s[22:23]
	s_or_b64 s[0:1], s[0:1], vcc
	s_and_b64 vcc, exec, s[0:1]
	s_cbranch_vccnz .Lsf_rare
; template <int MODE, bool MASK, bool WITH_O>
; DI void attn_tile_t(lptr Kt, lptr Vt, const bf16x8 (&qf)[4], f32x16& o0, f32x16& o1, RowState& rs, const TP& tp, int lane) {
;     ...
;     } else {
;         const int i = lane & 31;
;         lptr vp = Vt + i * KPB + hi * 16;
;         float sum = 0.f;
;     ...
;         PV_STEP(s0, 0, 0) PV_STEP(s0, 8, 32) PV_STEP(s1, 0, 64) PV_STEP(s1, 8, 96)
;     ...
;         rs.l += sum;
	v_exp_f32_e32 v252, v34
	v_exp_f32_e32 v103, v35
	v_exp_f32_e32 v111, v36
	v_exp_f32_e32 v105, v37
	v_add_f32_e32 v106, 0, v252
	v_add_f32_e32 v106, v103, v106
	v_add_f32_e32 v104, v111, v106
	v_exp_f32_e32 v106, v38
	v_exp_f32_e32 v107, v39
	v_add_u32_e32 v228, s33, v172
	v_exp_f32_e32 v108, v40
	ds_read_b128 v[236:239], v228 offset:18432
	ds_read_b128 v[240:243], v228 offset:23040
	v_add_f32_e32 v104, v105, v104
	v_exp_f32_e32 v109, v41
	v_add_f32_e32 v104, v106, v104
	v_add_f32_e32 v104, v107, v104
	v_add_f32_e32 v104, v108, v104
	v_add_f32_e32 v110, v109, v104
	v_cvt_pk_bf16_f32 v104, v252, v103
	v_cvt_pk_bf16_f32 v105, v111, v105
	v_cvt_pk_bf16_f32 v106, v106, v107
	v_cvt_pk_bf16_f32 v107, v108, v109
	s_or_b64 s[22:23], s[22:23], s[28:29]
	s_waitcnt lgkmcnt(1)
	v_mfma_f32_32x32x16_bf16 v[18:33], v[236:239], v[104:107], v[18:33]
	s_waitcnt lgkmcnt(0)
	v_mfma_f32_32x32x16_bf16 v[2:17], v[240:243], v[104:107], v[2:17]
	v_exp_f32_e32 v252, v42
	v_exp_f32_e32 v43, v43
	v_exp_f32_e32 v103, v44
	v_exp_f32_e32 v44, v45
	v_add_f32_e32 v229, v252, v110
	v_exp_f32_e32 v45, v46
	v_add_f32_e32 v229, v43, v229
	v_exp_f32_e32 v46, v47
	v_add_f32_e32 v42, v103, v229
	v_exp_f32_e32 v47, v48
	ds_read_b128 v[236:239], v228 offset:18464
	ds_read_b128 v[240:243], v228 offset:23072
	v_add_f32_e32 v42, v44, v42
	v_exp_f32_e32 v48, v49
	v_add_f32_e32 v42, v45, v42
	v_add_f32_e32 v42, v46, v42
	v_add_f32_e32 v42, v47, v42
	v_add_f32_e32 v229, v48, v42
	v_cvt_pk_bf16_f32 v42, v252, v43
	v_cvt_pk_bf16_f32 v43, v103, v44
	v_cvt_pk_bf16_f32 v44, v45, v46
	v_cvt_pk_bf16_f32 v45, v47, v48
	s_waitcnt lgkmcnt(1)
	s_nop 0
	v_mfma_f32_32x32x16_bf16 v[18:33], v[236:239], v[42:45], v[18:33]
	s_waitcnt lgkmcnt(0)
	v_mfma_f32_32x32x16_bf16 v[2:17], v[240:243], v[42:45], v[2:17]
	v_exp_f32_e32 v230, v50
	v_exp_f32_e32 v51, v51
	v_exp_f32_e32 v231, v52
	v_exp_f32_e32 v52, v53
	v_add_f32_e32 v229, v230, v229
	v_exp_f32_e32 v53, v54
	v_add_f32_e32 v229, v51, v229
	v_exp_f32_e32 v54, v55
	v_add_f32_e32 v50, v231, v229
	v_exp_f32_e32 v55, v56
	ds_read_b128 v[42:45], v228 offset:18496
	ds_read_b128 v[46:49], v228 offset:23104
	v_add_f32_e32 v50, v52, v50
	v_exp_f32_e32 v41, v57
	v_add_f32_e32 v50, v53, v50
	v_add_f32_e32 v50, v54, v50
	v_add_f32_e32 v50, v55, v50
	v_add_f32_e32 v56, v41, v50
	v_cvt_pk_bf16_f32 v50, v230, v51
	v_cvt_pk_bf16_f32 v51, v231, v52
	v_cvt_pk_bf16_f32 v52, v53, v54
	v_cvt_pk_bf16_f32 v53, v55, v41
	s_waitcnt lgkmcnt(1)
	s_nop 0
	v_mfma_f32_32x32x16_bf16 v[18:33], v[42:45], v[50:53], v[18:33]
	s_waitcnt lgkmcnt(0)
	v_mfma_f32_32x32x16_bf16 v[2:17], v[46:49], v[50:53], v[2:17]
	v_exp_f32_e32 v38, v58
	v_exp_f32_e32 v34, v59
	v_exp_f32_e32 v0, v60
	v_exp_f32_e32 v35, v61
	v_add_f32_e32 v41, v38, v56
	v_exp_f32_e32 v36, v62
	ds_read_b128 v[42:45], v228 offset:18528
	ds_read_b128 v[46:49], v228 offset:23136
	v_add_f32_e32 v41, v34, v41
	v_exp_f32_e32 v37, v63
	v_exp_f32_e32 v39, v64
	v_exp_f32_e32 v40, v65
	v_add_f32_e32 v41, v0, v41
	v_add_f32_e32 v41, v35, v41
	v_add_f32_e32 v41, v36, v41
	v_add_f32_e32 v41, v37, v41
	v_cvt_pk_bf16_f32 v34, v38, v34
	v_cvt_pk_bf16_f32 v35, v0, v35
	v_cvt_pk_bf16_f32 v36, v36, v37
	v_cvt_pk_bf16_f32 v37, v39, v40
	v_add_f32_e32 v41, v39, v41
	v_add_f32_e32 v41, v40, v41
	s_waitcnt lgkmcnt(1)
	v_mfma_f32_32x32x16_bf16 v[18:33], v[42:45], v[34:37], v[18:33]
	s_waitcnt lgkmcnt(0)
	v_mfma_f32_32x32x16_bf16 v[2:17], v[46:49], v[34:37], v[2:17]
	v_add_f32_e32 v100, v100, v41
	s_branch .LBB0_618
